# gate: XCD-local balanced unit map (kpart of one (b,h) shared in one L2), replaces the xor balance
# baseline (speedup 1.0000x reference)
.LBB0_1086:
	s_and_b32 s64, s11, 7
	s_lshl_b32 s64, s64, 8
	s_lshr_b32 s65, s11, 3
	s_or_b32 s64, s64, s65
	s_bfe_u32 s65, s11, 0x10009
	s_mul_i32 s65, s65, 31
	s_xor_b32 s64, s64, s65
	s_and_b32 s15, s64, 31
	s_lshl_b32 s33, s15, 6
	s_and_b32 s14, s64, 31
	v_cmp_gt_i32_e32 vcc, s33, v0
	s_barrier
	s_and_saveexec_b64 s[2:3], vcc
	s_cbranch_execz .LBB0_1101
	s_lshl_b32 s4, s14, 6
	v_max_i32_e32 v4, s4, v1
	v_add_u32_e32 v6, v4, v70
	s_and_b32 s35, s64, 0xffffffe0
	v_cmp_lt_u32_e32 vcc, s1, v6
	s_mov_b64 s[16:17], -1
	v_mov_b32_e32 v4, v0
	v_mov_b32_e32 v5, v71
	s_and_saveexec_b64 s[4:5], vcc
	s_cbranch_execz .LBB0_1098
	v_lshrrev_b32_e32 v6, 8, v6
	v_add_u32_e32 v4, -1, v6
	v_lshrrev_b32_e32 v7, 1, v4
	v_cmp_lt_u32_e32 vcc, 5, v4
	v_mov_b32_e32 v11, 0
	v_add_u32_e32 v8, 1, v7
	v_mov_b64_e32 v[4:5], v[0:1]
	s_and_saveexec_b64 s[16:17], vcc
	s_cbranch_execz .LBB0_1092
	v_and_b32_e32 v9, -4, v8
	s_mov_b32 s38, 0
	s_mov_b64 s[36:37], 0
	v_mov_b32_e32 v10, v72
	v_mov_b64_e32 v[4:5], v[0:1]

.LBB0_1101:
	s_or_b64 exec, exec, s[2:3]
	s_ashr_i32 s2, s64, 5
	v_lshl_add_u32 v4, s15, 8, v0
	s_ashr_i32 s3, s2, 31
	s_lshl_b64 s[2:3], s[2:3], 13
	v_ashrrev_i32_e32 v5, 31, v4
	s_cmp_eq_u32 s15, 0
	v_lshl_add_u64 v[4:5], s[2:3], 0, v[4:5]
	s_waitcnt lgkmcnt(0)
	s_barrier
	s_cbranch_scc1 .LBB0_1111
	v_lshlrev_b64 v[6:7], 7, v[4:5]
	v_lshl_add_u64 v[6:7], s[6:7], 0, v[6:7]
	global_load_dwordx4 v[10:13], v[6:7], off
	global_load_dwordx4 v[18:21], v[6:7], off offset:16
	global_load_dwordx4 v[26:29], v[6:7], off offset:32
	global_load_dwordx4 v[34:37], v[6:7], off offset:48
	global_load_dwordx4 v[42:45], v[6:7], off offset:64
	global_load_dwordx4 v[50:53], v[6:7], off offset:80
	global_load_dwordx4 v[58:61], v[6:7], off offset:96
	global_load_dwordx4 v[66:69], v[6:7], off offset:112
	v_mov_b32_e32 v77, 0xff
	s_mov_b32 s15, 0
	v_mov_b32_e32 v76, 0xff61b1e6
	s_mov_b32 s33, 16
	v_mov_b32_e32 v75, 0xff61b1e6
	v_mov_b32_e32 v73, 0xff
	v_mov_b32_e32 v74, 0xff
	v_mov_b32_e32 v78, 0xff61b1e6
	s_waitcnt vmcnt(7)
	v_lshlrev_b32_e32 v6, 16, v10
	v_and_b32_e32 v7, 0xffff0000, v10
	v_lshlrev_b32_e32 v8, 16, v11
	v_and_b32_e32 v9, 0xffff0000, v11
	v_lshlrev_b32_e32 v10, 16, v12
	v_and_b32_e32 v11, 0xffff0000, v12
	v_lshlrev_b32_e32 v12, 16, v13
	v_and_b32_e32 v13, 0xffff0000, v13
	s_waitcnt vmcnt(6)
	v_lshlrev_b32_e32 v14, 16, v18
	v_and_b32_e32 v15, 0xffff0000, v18
	v_lshlrev_b32_e32 v16, 16, v19
	v_and_b32_e32 v17, 0xffff0000, v19
	v_lshlrev_b32_e32 v18, 16, v20
	v_and_b32_e32 v19, 0xffff0000, v20
	v_lshlrev_b32_e32 v20, 16, v21
	v_and_b32_e32 v21, 0xffff0000, v21
	s_waitcnt vmcnt(5)
	v_lshlrev_b32_e32 v22, 16, v26
	v_and_b32_e32 v23, 0xffff0000, v26
	v_lshlrev_b32_e32 v24, 16, v27
	v_and_b32_e32 v25, 0xffff0000, v27
	v_lshlrev_b32_e32 v26, 16, v28
	v_and_b32_e32 v27, 0xffff0000, v28
	v_lshlrev_b32_e32 v28, 16, v29
	v_and_b32_e32 v29, 0xffff0000, v29
	s_waitcnt vmcnt(4)
	v_lshlrev_b32_e32 v30, 16, v34
	v_and_b32_e32 v31, 0xffff0000, v34
	v_lshlrev_b32_e32 v32, 16, v35
	v_and_b32_e32 v33, 0xffff0000, v35
	v_lshlrev_b32_e32 v34, 16, v36
	v_and_b32_e32 v35, 0xffff0000, v36
	v_lshlrev_b32_e32 v36, 16, v37
	v_and_b32_e32 v37, 0xffff0000, v37
	s_waitcnt vmcnt(3)
	v_lshlrev_b32_e32 v38, 16, v42
	v_and_b32_e32 v39, 0xffff0000, v42
	v_lshlrev_b32_e32 v40, 16, v43
	v_and_b32_e32 v41, 0xffff0000, v43
	v_lshlrev_b32_e32 v42, 16, v44
	v_and_b32_e32 v43, 0xffff0000, v44
	v_lshlrev_b32_e32 v44, 16, v45
	v_and_b32_e32 v45, 0xffff0000, v45
	s_waitcnt vmcnt(2)
	v_lshlrev_b32_e32 v46, 16, v50
	v_and_b32_e32 v47, 0xffff0000, v50
	v_lshlrev_b32_e32 v48, 16, v51
	v_and_b32_e32 v49, 0xffff0000, v51
	v_lshlrev_b32_e32 v50, 16, v52
	v_and_b32_e32 v51, 0xffff0000, v52
	v_lshlrev_b32_e32 v52, 16, v53
	v_and_b32_e32 v53, 0xffff0000, v53
	s_waitcnt vmcnt(1)
	v_lshlrev_b32_e32 v54, 16, v58
	v_and_b32_e32 v55, 0xffff0000, v58
	v_lshlrev_b32_e32 v56, 16, v59
	v_and_b32_e32 v57, 0xffff0000, v59
	v_lshlrev_b32_e32 v58, 16, v60
	v_and_b32_e32 v59, 0xffff0000, v60
	v_lshlrev_b32_e32 v60, 16, v61
	v_and_b32_e32 v61, 0xffff0000, v61
	s_waitcnt vmcnt(0)
	v_lshlrev_b32_e32 v62, 16, v66
	v_and_b32_e32 v63, 0xffff0000, v66
	v_lshlrev_b32_e32 v64, 16, v67
	v_and_b32_e32 v65, 0xffff0000, v67
	v_lshlrev_b32_e32 v66, 16, v68
	v_and_b32_e32 v67, 0xffff0000, v68
	v_lshlrev_b32_e32 v68, 16, v69
	v_and_b32_e32 v69, 0xffff0000, v69
